# M4B gate loads hoisted above the last two K-steps of each branch
# speedup vs baseline: 1.0035x; 1.0035x over previous
; #define MFMA(a, b, c) __builtin_amdgcn_mfma_f32_32x32x16_bf16((a), (b), (c), 0, 0, 0)
; DI size_t gate_off(size_t row4, int col) { return (((row4 >> 2) * 128 + (size_t)(col >> 5)) * 32 + (size_t)(col & 31)) * 4; }
; template <int NB, int NS>
; DI void gemm_core(f32x16 (&acc)[NB][2][NS], const u16* __restrict__ A, long lda, long akcs,
;                   const u16* __restrict__ B0, const u16* __restrict__ B1, long ldb, int K, char* smem) {
;     ...
;   for (int kt = 0; kt < nk; ++kt) {
;     const int s = kt & 1;
;     if (kt + 1 < nk) GEMM_SSTORE(s ^ 1)
;     if (kt + 2 < nk) GEMM_GLOAD(kt + 2)
;     __builtin_amdgcn_sched_barrier(0);
;     const char* base = smem + s * STAGE;
; #pragma unroll
;     for (int kk = 0; kk < 4; ++kk) {
;       bf16x8 af[2], bfr[NB][NS];
; #pragma unroll
;       for (int ms = 0; ms < 2; ++ms) {
;         const int row = wm * 64 + ms * 32 + lr, ch = kk * 2 + lh;
;         af[ms] = *(const bf16x8*)(base + row * 128 + ((ch ^ ((row >> 1) & 7)) << 4));
;       }
; #pragma unroll
;       for (int b = 0; b < NB; ++b)
; #pragma unroll
;         for (int ns = 0; ns < NS; ++ns) {
;           const int row = wn * (32 * NS) + ns * 32 + lr, ch = kk * 2 + lh;
;           bfr[b][ns] = *(const bf16x8*)(base + A_BYTES + b * B_BYTES + row * 128 + ((ch ^ ((row >> 1) & 7)) << 4));
;         }
; #pragma unroll
;       for (int b = 0; b < NB; ++b)
; #pragma unroll
;         for (int ms = 0; ms < 2; ++ms)
; #pragma unroll
;           for (int ns = 0; ns < NS; ++ns) acc[b][ms][ns] = MFMA(af[ms], bfr[b][ns], acc[b][ms][ns]);
;     }
;     __syncthreads();
; DI void phase_m4b(const Params& p, int l, char* smem) {
;     ...
;           for (int gq = 0; gq < 4; ++gq) {
;             const size_t row = (size_t)mt * 256 + wm * 64 + ms * 32 + 8 * gq + 4 * lh;
;             const int col = nt * 128 + wn * 64 + ns * 32 + lr;
;             const unsigned long long gq64 = __builtin_nontemporal_load((const unsigned long long*)(gt + gate_off(row, br * 1024 + col)));
.LBB0_135:
	s_and_b32 s35, s6, 1
	s_xor_b32 s42, s35, 1
	s_mul_i32 s42, s42, 0xc000
	v_add_u32_e32 v0, s42, v165
	s_waitcnt vmcnt(4)
	ds_write_b128 v0, v[66:69]
	s_waitcnt vmcnt(0)
	ds_write_b128 v0, v[78:81] offset:8192
	ds_write_b128 v0, v[74:77] offset:16384
	ds_write_b128 v0, v[70:73] offset:24576
	ds_write_b128 v0, v[82:85] offset:32768
	ds_write_b128 v0, v[86:89] offset:40960
	v_lshl_add_u64 v[70:71], v[92:93], 0, s[10:11]
	s_mov_b32 s42, 0x14b14000
	v_add_co_u32_e32 v66, vcc, s42, v70
	s_mov_b32 s42, 0x14b54000
	s_nop 0
	v_addc_co_u32_e32 v67, vcc, 0, v71, vcc
	v_add_co_u32_e32 v72, vcc, s42, v70
	s_mov_b32 s42, 0x14b94000
	s_nop 0
	v_addc_co_u32_e32 v73, vcc, 0, v71, vcc
	global_load_dwordx4 v[78:81], v[72:73], off offset:3328
	v_add_co_u32_e32 v72, vcc, s42, v70
	s_mov_b32 s42, 0x14bd4000
	s_nop 0
	v_addc_co_u32_e32 v73, vcc, 0, v71, vcc
	v_add_co_u32_e32 v70, vcc, s42, v70
	v_lshl_add_u64 v[86:87], v[90:91], 0, s[10:11]
	s_nop 0
	v_addc_co_u32_e32 v71, vcc, 0, v71, vcc
	s_mov_b32 s42, 0x3180000
	v_add_co_u32_e32 v82, vcc, s42, v86
	s_mov_b32 s42, 0x3190000
	s_nop 0
	v_addc_co_u32_e32 v83, vcc, 0, v87, vcc
	v_add_co_u32_e32 v86, vcc, s42, v86
	global_load_dwordx4 v[66:69], v[66:67], off offset:3328
	s_nop 0
	v_addc_co_u32_e32 v87, vcc, 0, v87, vcc
	global_load_dwordx4 v[74:77], v[72:73], off offset:3328
	s_add_i32 s6, s6, 1
	global_load_dwordx4 v[70:73], v[70:71], off offset:3328
	s_nop 0
	global_load_dwordx4 v[82:85], v[82:83], off offset:256
	s_nop 0
	global_load_dwordx4 v[86:89], v[86:87], off offset:256
	s_mul_i32 s35, s35, 0xc000
	s_add_i32 s35, s35, 0
	v_add_u32_e32 v0, s35, v163
	v_add_u32_e32 v178, v0, v164
	ds_read_b128 v[166:169], v178
	v_add_u32_e32 v0, v0, v159
	ds_read_b128 v[170:173], v0 offset:32768
	ds_read_b128 v[174:177], v0 offset:36864
	v_add_u32_e32 v0, s35, v162
	s_add_u32 s10, s10, 0x80
	s_addc_u32 s11, s11, 0
	s_cmpk_lg_i32 s10, 0x300
	s_waitcnt lgkmcnt(1)
	v_mfma_f32_32x32x16_bf16 v[50:65], v[166:169], v[170:173], v[50:65]
	s_waitcnt lgkmcnt(0)
	v_mfma_f32_32x32x16_bf16 v[34:49], v[166:169], v[174:177], v[34:49]
	ds_read_b128 v[166:169], v178 offset:4096
	v_add_u32_e32 v178, v0, v164
	v_add_u32_e32 v0, v0, v159
	s_waitcnt lgkmcnt(0)
	v_mfma_f32_32x32x16_bf16 v[18:33], v[166:169], v[170:173], v[18:33]
	ds_read_b128 v[170:173], v0 offset:32768
	v_mfma_f32_32x32x16_bf16 v[2:17], v[166:169], v[174:177], v[2:17]
	ds_read_b128 v[166:169], v178
	ds_read_b128 v[174:177], v0 offset:36864
	v_add_u32_e32 v0, s35, v161
	s_waitcnt lgkmcnt(1)
	v_mfma_f32_32x32x16_bf16 v[50:65], v[166:169], v[170:173], v[50:65]
	s_waitcnt lgkmcnt(0)
	v_mfma_f32_32x32x16_bf16 v[34:49], v[166:169], v[174:177], v[34:49]
	ds_read_b128 v[166:169], v178 offset:4096
	v_add_u32_e32 v178, v0, v164
	v_add_u32_e32 v0, v0, v159
	s_waitcnt lgkmcnt(0)
	v_mfma_f32_32x32x16_bf16 v[18:33], v[166:169], v[170:173], v[18:33]
	ds_read_b128 v[170:173], v0 offset:32768
	v_mfma_f32_32x32x16_bf16 v[2:17], v[166:169], v[174:177], v[2:17]
	ds_read_b128 v[166:169], v178
	ds_read_b128 v[174:177], v0 offset:36864
	v_add_u32_e32 v0, s35, v160
	s_waitcnt lgkmcnt(1)
	v_mfma_f32_32x32x16_bf16 v[50:65], v[166:169], v[170:173], v[50:65]
	s_waitcnt lgkmcnt(0)
	v_mfma_f32_32x32x16_bf16 v[34:49], v[166:169], v[174:177], v[34:49]
	ds_read_b128 v[166:169], v178 offset:4096
	v_add_u32_e32 v178, v0, v164
	v_add_u32_e32 v0, v0, v159
	s_waitcnt lgkmcnt(0)
	v_mfma_f32_32x32x16_bf16 v[18:33], v[166:169], v[170:173], v[18:33]
	ds_read_b128 v[170:173], v0 offset:32768
	v_mfma_f32_32x32x16_bf16 v[2:17], v[166:169], v[174:177], v[2:17]
	ds_read_b128 v[166:169], v178
	ds_read_b128 v[174:177], v0 offset:36864
	s_waitcnt lgkmcnt(1)
	v_mfma_f32_32x32x16_bf16 v[50:65], v[166:169], v[170:173], v[50:65]
	s_waitcnt lgkmcnt(0)
	v_mfma_f32_32x32x16_bf16 v[34:49], v[166:169], v[174:177], v[34:49]
	ds_read_b128 v[166:169], v178 offset:4096
	s_waitcnt lgkmcnt(0)
	s_barrier
	v_mfma_f32_32x32x16_bf16 v[18:33], v[166:169], v[170:173], v[18:33]
	v_mfma_f32_32x32x16_bf16 v[2:17], v[166:169], v[174:177], v[2:17]
	s_cbranch_scc1 .LBB0_135
	v_add_u32_e32 v0, 0x10000, v165
	s_waitcnt vmcnt(4)
	ds_write_b128 v165, v[66:69] offset:49152
	ds_write_b128 v165, v[78:81] offset:57344
	s_waitcnt vmcnt(3)
	ds_write_b128 v0, v[74:77]
	v_add_u32_e32 v0, 0x12000, v165
	s_waitcnt vmcnt(2)
	ds_write_b128 v0, v[70:73]
	v_add_u32_e32 v0, 0x14000, v165
	s_waitcnt vmcnt(1)
	ds_write_b128 v0, v[82:85]
	v_add_u32_e32 v0, 0x16000, v165
	s_waitcnt vmcnt(0)
	ds_write_b128 v0, v[86:89]
	s_add_i32 s98, s7, s36
	v_lshrrev_b32_e32 v248, 1, v196
	v_and_b32_e32 v248, 0xffffffc0, v248
	v_lshrrev_b32_e32 v249, 3, v196
	v_and_b32_e32 v249, 4, v249
	v_add3_u32 v248, v248, v249, s62
	v_lshlrev_b32_e32 v248, 13, v248
	v_and_b32_e32 v249, 64, v196
	v_or_b32_e32 v249, s98, v249
	v_lshrrev_b32_e32 v249, 5, v249
	v_lshl_add_u32 v248, v249, 8, v248
	v_and_b32_e32 v249, 31, v196
	v_lshl_add_u32 v248, v249, 3, v248
	global_load_dwordx2 v[216:217], v248, s[0:1] nt
	v_add_u32_e32 v249, 0x10000, v248
	global_load_dwordx2 v[218:219], v249, s[0:1] nt
	v_add_u32_e32 v249, 0x20000, v248
	global_load_dwordx2 v[220:221], v249, s[0:1] nt
	v_add_u32_e32 v249, 0x30000, v248
	global_load_dwordx2 v[222:223], v249, s[0:1] nt
	global_load_dwordx2 v[224:225], v248, s[0:1] offset:256 nt
	v_add_u32_e32 v249, 0x10000, v248
	global_load_dwordx2 v[226:227], v249, s[0:1] offset:256 nt
	v_add_u32_e32 v249, 0x20000, v248
	global_load_dwordx2 v[228:229], v249, s[0:1] offset:256 nt
	v_add_u32_e32 v249, 0x30000, v248
	global_load_dwordx2 v[230:231], v249, s[0:1] offset:256 nt
	v_add_u32_e32 v249, 0x40000, v248
	global_load_dwordx2 v[232:233], v249, s[0:1] nt
	v_add_u32_e32 v249, 0x50000, v248
	global_load_dwordx2 v[234:235], v249, s[0:1] nt
	v_add_u32_e32 v249, 0x60000, v248
	global_load_dwordx2 v[236:237], v249, s[0:1] nt
	v_add_u32_e32 v249, 0x70000, v248
	global_load_dwordx2 v[238:239], v249, s[0:1] nt
	v_add_u32_e32 v249, 0x40000, v248
	global_load_dwordx2 v[240:241], v249, s[0:1] offset:256 nt
	v_add_u32_e32 v249, 0x50000, v248
	global_load_dwordx2 v[242:243], v249, s[0:1] offset:256 nt
	v_add_u32_e32 v249, 0x60000, v248
	global_load_dwordx2 v[244:245], v249, s[0:1] offset:256 nt
	v_add_u32_e32 v249, 0x70000, v248
	global_load_dwordx2 v[246:247], v249, s[0:1] offset:256 nt
	v_add_u32_e32 v0, 0, v163
	v_add_u32_e32 v78, v0, v164
	ds_read_b128 v[66:69], v78
	v_add_u32_e32 v0, v0, v159
	ds_read_b128 v[70:73], v0 offset:32768
	ds_read_b128 v[74:77], v0 offset:36864
	v_add_u32_e32 v0, 0, v162
	v_add_u32_e32 v82, v0, v164
	v_add_u32_e32 v0, v0, v159
	s_waitcnt lgkmcnt(1)
; #define MFMA(a, b, c) __builtin_amdgcn_mfma_f32_32x32x16_bf16((a), (b), (c), 0, 0, 0)
; DI size_t gate_off(size_t row4, int col) { return (((row4 >> 2) * 128 + (size_t)(col >> 5)) * 32 + (size_t)(col & 31)) * 4; }
; template <int NB, int NS>
; DI void gemm_core(f32x16 (&acc)[NB][2][NS], const u16* __restrict__ A, long lda, long akcs,
;                   const u16* __restrict__ B0, const u16* __restrict__ B1, long ldb, int K, char* smem) {
;     ...
;     const char* base = smem + s * STAGE;
; #pragma unroll
;     for (int kk = 0; kk < 4; ++kk) {
;       bf16x8 af[2], bfr[NB][NS];
; #pragma unroll
;       for (int ms = 0; ms < 2; ++ms) {
;         const int row = wm * 64 + ms * 32 + lr, ch = kk * 2 + lh;
;         af[ms] = *(const bf16x8*)(base + row * 128 + ((ch ^ ((row >> 1) & 7)) << 4));
;       }
; #pragma unroll
;       for (int b = 0; b < NB; ++b)
; #pragma unroll
;         for (int ns = 0; ns < NS; ++ns) {
;           const int row = wn * (32 * NS) + ns * 32 + lr, ch = kk * 2 + lh;
;           bfr[b][ns] = *(const bf16x8*)(base + A_BYTES + b * B_BYTES + row * 128 + ((ch ^ ((row >> 1) & 7)) << 4));
;         }
; #pragma unroll
;       for (int b = 0; b < NB; ++b)
; #pragma unroll
;         for (int ms = 0; ms < 2; ++ms)
; #pragma unroll
;           for (int ns = 0; ns < NS; ++ns) acc[b][ms][ns] = MFMA(af[ms], bfr[b][ns], acc[b][ms][ns]);
;     }
;     __syncthreads();
; DI void phase_m4b(const Params& p, int l, char* smem) {
;     ...
;           for (int gq = 0; gq < 4; ++gq) {
;             const size_t row = (size_t)mt * 256 + wm * 64 + ms * 32 + 8 * gq + 4 * lh;
;             const int col = nt * 128 + wn * 64 + ns * 32 + lr;
;             const unsigned long long gq64 = __builtin_nontemporal_load((const unsigned long long*)(gt + gate_off(row, br * 1024 + col)));
;             uint2 gv; gv.x = (unsigned)gq64; gv.y = (unsigned)(gq64 >> 32);
;             accm[ms][ns][4 * gq] += __uint_as_float(gv.x << 16) * ay[0][ms][ns][4 * gq];
;             accm[ms][ns][4 * gq + 1] += __uint_as_float(gv.x & 0xffff0000u) * ay[0][ms][ns][4 * gq + 1];
;             accm[ms][ns][4 * gq + 2] += __uint_as_float(gv.y << 16) * ay[0][ms][ns][4 * gq + 2];
;             accm[ms][ns][4 * gq + 3] += __uint_as_float(gv.y & 0xffff0000u) * ay[0][ms][ns][4 * gq + 3];
	v_mfma_f32_32x32x16_bf16 v[50:65], v[66:69], v[70:73], v[50:65]
	s_waitcnt lgkmcnt(0)
	v_mfma_f32_32x32x16_bf16 v[34:49], v[66:69], v[74:77], v[34:49]
	ds_read_b128 v[66:69], v78 offset:4096
	s_waitcnt lgkmcnt(0)
	v_mfma_f32_32x32x16_bf16 v[18:33], v[66:69], v[70:73], v[18:33]
	ds_read_b128 v[70:73], v0 offset:32768
	v_mfma_f32_32x32x16_bf16 v[2:17], v[66:69], v[74:77], v[2:17]
	ds_read_b128 v[66:69], v82
	ds_read_b128 v[74:77], v0 offset:36864
	v_add_u32_e32 v0, 0, v161
	v_add_u32_e32 v83, v0, v164
	v_add_u32_e32 v0, v0, v159
	s_waitcnt lgkmcnt(1)
	v_mfma_f32_32x32x16_bf16 v[50:65], v[66:69], v[70:73], v[50:65]
	s_waitcnt lgkmcnt(0)
	v_mfma_f32_32x32x16_bf16 v[34:49], v[66:69], v[74:77], v[34:49]
	ds_read_b128 v[66:69], v82 offset:4096
	s_waitcnt lgkmcnt(0)
	v_mfma_f32_32x32x16_bf16 v[18:33], v[66:69], v[70:73], v[18:33]
	ds_read_b128 v[70:73], v0 offset:32768
	v_mfma_f32_32x32x16_bf16 v[2:17], v[66:69], v[74:77], v[2:17]
	ds_read_b128 v[66:69], v83
	ds_read_b128 v[74:77], v0 offset:36864
	v_add_u32_e32 v0, 0, v160
	v_add_u32_e32 v84, v0, v164
	v_add_u32_e32 v0, v0, v159
	s_waitcnt lgkmcnt(1)
	v_mfma_f32_32x32x16_bf16 v[50:65], v[66:69], v[70:73], v[50:65]
	s_waitcnt lgkmcnt(0)
	v_mfma_f32_32x32x16_bf16 v[34:49], v[66:69], v[74:77], v[34:49]
	ds_read_b128 v[66:69], v83 offset:4096
	s_waitcnt lgkmcnt(0)
	v_mfma_f32_32x32x16_bf16 v[18:33], v[66:69], v[70:73], v[18:33]
	ds_read_b128 v[70:73], v0 offset:32768
	v_mfma_f32_32x32x16_bf16 v[2:17], v[66:69], v[74:77], v[2:17]
	ds_read_b128 v[66:69], v84
	ds_read_b128 v[74:77], v0 offset:36864
	s_waitcnt lgkmcnt(1)
	v_mfma_f32_32x32x16_bf16 v[50:65], v[66:69], v[70:73], v[50:65]
	s_waitcnt lgkmcnt(0)
	v_mfma_f32_32x32x16_bf16 v[34:49], v[66:69], v[74:77], v[34:49]
	ds_read_b128 v[66:69], v84 offset:4096
	s_waitcnt lgkmcnt(0)
	s_barrier
	v_mfma_f32_32x32x16_bf16 v[18:33], v[66:69], v[70:73], v[18:33]
	v_mfma_f32_32x32x16_bf16 v[2:17], v[66:69], v[74:77], v[2:17]
	s_add_i32 s6, 0, 0x14000
	v_add3_u32 v0, s6, v163, v159
	ds_read_b128 v[66:69], v78 offset:49152
	ds_read_b128 v[70:73], v78 offset:53248
	ds_read_b128 v[74:77], v0
	ds_read_b128 v[78:81], v0 offset:4096
	v_add3_u32 v0, s6, v162, v159
	s_add_i32 s7, s7, s36
	s_waitcnt lgkmcnt(1)
	v_mfma_f32_32x32x16_bf16 v[50:65], v[66:69], v[74:77], v[50:65]
	s_add_i32 s41, s41, 1
	s_add_u32 s4, s4, 0x100000
	s_addc_u32 s5, s5, 0
	s_add_u32 s8, s8, 0x400
	s_addc_u32 s9, s9, 0
	s_cmp_eq_u32 s41, 4
	s_waitcnt lgkmcnt(0)
	v_mfma_f32_32x32x16_bf16 v[34:49], v[66:69], v[78:81], v[34:49]
	v_mfma_f32_32x32x16_bf16 v[18:33], v[70:73], v[74:77], v[18:33]
	v_mfma_f32_32x32x16_bf16 v[2:17], v[70:73], v[78:81], v[2:17]
	ds_read_b128 v[66:69], v82 offset:49152
	ds_read_b128 v[70:73], v82 offset:53248
	ds_read_b128 v[74:77], v0
	ds_read_b128 v[78:81], v0 offset:4096
	v_add3_u32 v0, s6, v161, v159
	s_waitcnt lgkmcnt(1)
	v_mfma_f32_32x32x16_bf16 v[50:65], v[66:69], v[74:77], v[50:65]
	s_waitcnt lgkmcnt(0)
	v_mfma_f32_32x32x16_bf16 v[34:49], v[66:69], v[78:81], v[34:49]
	v_mfma_f32_32x32x16_bf16 v[18:33], v[70:73], v[74:77], v[18:33]
	v_mfma_f32_32x32x16_bf16 v[2:17], v[70:73], v[78:81], v[2:17]
	ds_read_b128 v[66:69], v83 offset:49152
	ds_read_b128 v[70:73], v83 offset:53248
	ds_read_b128 v[74:77], v0
	ds_read_b128 v[78:81], v0 offset:4096
	v_add3_u32 v0, s6, v160, v159
	s_waitcnt lgkmcnt(1)
	v_mfma_f32_32x32x16_bf16 v[50:65], v[66:69], v[74:77], v[50:65]
	s_waitcnt lgkmcnt(0)
	v_mfma_f32_32x32x16_bf16 v[34:49], v[66:69], v[78:81], v[34:49]
	v_mfma_f32_32x32x16_bf16 v[18:33], v[70:73], v[74:77], v[18:33]
	v_mfma_f32_32x32x16_bf16 v[2:17], v[70:73], v[78:81], v[2:17]
	ds_read_b128 v[66:69], v84 offset:49152
	ds_read_b128 v[70:73], v84 offset:53248
	ds_read_b128 v[74:77], v0
	ds_read_b128 v[78:81], v0 offset:4096
	v_mov_b32_e32 v0, v196
	s_waitcnt lgkmcnt(0)
	s_barrier
	v_mfma_f32_32x32x16_bf16 v[50:65], v[66:69], v[74:77], v[50:65]
	v_mfma_f32_32x32x16_bf16 v[34:49], v[66:69], v[78:81], v[34:49]
	v_ashrrev_i32_e32 v66, 1, v0
	v_and_b32_e32 v66, 0xffffffc0, v66
	v_ashrrev_i32_e32 v67, 31, v66
	v_lshl_add_u64 v[68:69], v[66:67], 0, s[62:63]
	v_lshrrev_b32_e32 v66, 3, v0
	v_and_or_b32 v68, v66, 4, v68
	v_lshlrev_b64 v[68:69], 5, v[68:69]
	v_mfma_f32_32x32x16_bf16 v[18:33], v[70:73], v[74:77], v[18:33]
	v_and_b32_e32 v69, 0xffffff, v69
	v_and_b32_e32 v68, 0xfffff880, v68
	v_mfma_f32_32x32x16_bf16 v[2:17], v[70:73], v[78:81], v[2:17]
	v_and_or_b32 v70, v0, 64, s7
	v_lshlrev_b32_e32 v0, 3, v0
	v_and_b32_e32 v0, 0xf8, v0
	v_lshl_add_u64 v[66:67], s[0:1], 0, v[0:1]
	v_lshrrev_b32_e32 v0, 5, v70
	v_lshl_add_u64 v[70:71], v[68:69], 0, v[0:1]
	v_lshlrev_b64 v[70:71], 8, v[70:71]
	v_lshl_add_u64 v[70:71], v[66:67], 0, v[70:71]
	s_waitcnt vmcnt(15)
	v_lshlrev_b32_e32 v72, 16, v216
	v_fmac_f32_e32 v158, v50, v72
	v_and_b32_e32 v50, 0xffff0000, v216
	v_fmac_f32_e32 v157, v51, v50
	v_lshlrev_b32_e32 v50, 16, v217
	v_fmac_f32_e32 v156, v52, v50
	v_and_b32_e32 v50, 0xffff0000, v217
	v_or_b32_e32 v70, 0x100, v68
	v_mov_b32_e32 v71, v69
	v_fmac_f32_e32 v155, v53, v50
	v_lshl_add_u64 v[50:51], v[70:71], 0, v[0:1]
	v_lshlrev_b64 v[50:51], 8, v[50:51]
	v_lshl_add_u64 v[50:51], v[66:67], 0, v[50:51]
	v_mov_b32_e32 v53, v69
	s_waitcnt vmcnt(14)
	v_lshlrev_b32_e32 v52, 16, v218
	v_and_b32_e32 v50, 0xffff0000, v218
	v_fmac_f32_e32 v152, v55, v50
	v_lshlrev_b32_e32 v50, 16, v219
	v_fmac_f32_e32 v153, v54, v52
	v_fmac_f32_e32 v151, v56, v50
	v_and_b32_e32 v50, 0xffff0000, v219
	v_or_b32_e32 v54, 0x200, v68
	v_mov_b32_e32 v55, v69
	v_fmac_f32_e32 v150, v57, v50
	v_lshl_add_u64 v[50:51], v[54:55], 0, v[0:1]
	v_lshlrev_b64 v[50:51], 8, v[50:51]
	v_lshl_add_u64 v[50:51], v[66:67], 0, v[50:51]
	s_waitcnt vmcnt(13)
; DI size_t gate_off(size_t row4, int col) { return (((row4 >> 2) * 128 + (size_t)(col >> 5)) * 32 + (size_t)(col & 31)) * 4; }
; DI void phase_m4b(const Params& p, int l, char* smem) {
;     ...
;           for (int gq = 0; gq < 4; ++gq) {
;             const size_t row = (size_t)mt * 256 + wm * 64 + ms * 32 + 8 * gq + 4 * lh;
;             const int col = nt * 128 + wn * 64 + ns * 32 + lr;
;             const unsigned long long gq64 = __builtin_nontemporal_load((const unsigned long long*)(gt + gate_off(row, br * 1024 + col)));
;             uint2 gv; gv.x = (unsigned)gq64; gv.y = (unsigned)(gq64 >> 32);
;             accm[ms][ns][4 * gq] += __uint_as_float(gv.x << 16) * ay[0][ms][ns][4 * gq];
;             accm[ms][ns][4 * gq + 1] += __uint_as_float(gv.x & 0xffff0000u) * ay[0][ms][ns][4 * gq + 1];
;             accm[ms][ns][4 * gq + 2] += __uint_as_float(gv.y << 16) * ay[0][ms][ns][4 * gq + 2];
;             accm[ms][ns][4 * gq + 3] += __uint_as_float(gv.y & 0xffff0000u) * ay[0][ms][ns][4 * gq + 3];
;           }
	v_lshlrev_b32_e32 v52, 16, v220
	v_and_b32_e32 v50, 0xffff0000, v220
	v_fmac_f32_e32 v148, v59, v50
	v_lshlrev_b32_e32 v50, 16, v221
	v_fmac_f32_e32 v149, v58, v52
	v_fmac_f32_e32 v147, v60, v50
	v_and_b32_e32 v50, 0xffff0000, v221
	v_or_b32_e32 v52, 0x300, v68
	v_fmac_f32_e32 v146, v61, v50
	v_lshl_add_u64 v[50:51], v[52:53], 0, v[0:1]
	v_lshlrev_b64 v[50:51], 8, v[50:51]
	v_lshl_add_u64 v[50:51], v[66:67], 0, v[50:51]
	s_waitcnt vmcnt(12)
	v_lshlrev_b32_e32 v56, 16, v222
	v_and_b32_e32 v50, 0xffff0000, v222
	v_fmac_f32_e32 v144, v63, v50
	v_lshlrev_b32_e32 v50, 16, v223
	v_fmac_f32_e32 v143, v64, v50
	v_and_b32_e32 v50, 0xffff0000, v223
	v_fmac_f32_e32 v142, v65, v50
	v_or_b32_e32 v50, 1, v0
	v_mov_b32_e32 v51, v1
	v_fmac_f32_e32 v145, v62, v56
	v_lshl_add_u64 v[56:57], v[68:69], 0, v[50:51]
	v_lshlrev_b64 v[56:57], 8, v[56:57]
	v_lshl_add_u64 v[56:57], v[66:67], 0, v[56:57]
	s_waitcnt vmcnt(11)
	v_lshlrev_b32_e32 v58, 16, v224
	v_fmac_f32_e32 v141, v34, v58
	v_and_b32_e32 v34, 0xffff0000, v224
	v_fmac_f32_e32 v140, v35, v34
	v_lshlrev_b32_e32 v34, 16, v225
	v_fmac_f32_e32 v139, v36, v34
	v_and_b32_e32 v34, 0xffff0000, v225
	v_fmac_f32_e32 v138, v37, v34
	v_lshl_add_u64 v[34:35], v[70:71], 0, v[50:51]
	v_lshlrev_b64 v[34:35], 8, v[34:35]
	v_lshl_add_u64 v[34:35], v[66:67], 0, v[34:35]
	s_waitcnt vmcnt(10)
	v_lshlrev_b32_e32 v36, 16, v226
	v_and_b32_e32 v34, 0xffff0000, v226
	v_fmac_f32_e32 v136, v39, v34
	v_lshlrev_b32_e32 v34, 16, v227
	v_fmac_f32_e32 v135, v40, v34
	v_and_b32_e32 v34, 0xffff0000, v227
	v_fmac_f32_e32 v134, v41, v34
	v_lshl_add_u64 v[34:35], v[54:55], 0, v[50:51]
	v_lshlrev_b64 v[34:35], 8, v[34:35]
	v_lshl_add_u64 v[34:35], v[66:67], 0, v[34:35]
	v_fmac_f32_e32 v137, v38, v36
	s_waitcnt vmcnt(9)
	v_lshlrev_b32_e32 v36, 16, v228
	v_and_b32_e32 v34, 0xffff0000, v228
	v_fmac_f32_e32 v132, v43, v34
	v_lshlrev_b32_e32 v34, 16, v229
	v_fmac_f32_e32 v131, v44, v34
	v_and_b32_e32 v34, 0xffff0000, v229
	v_fmac_f32_e32 v130, v45, v34
	v_lshl_add_u64 v[34:35], v[52:53], 0, v[50:51]
	v_lshlrev_b64 v[34:35], 8, v[34:35]
	v_lshl_add_u64 v[34:35], v[66:67], 0, v[34:35]
	v_fmac_f32_e32 v133, v42, v36
	s_waitcnt vmcnt(8)
	v_lshlrev_b32_e32 v36, 16, v230
	v_and_b32_e32 v34, 0xffff0000, v230
	v_fmac_f32_e32 v128, v47, v34
	v_lshlrev_b32_e32 v34, 16, v231
	v_fmac_f32_e32 v127, v48, v34
	v_and_b32_e32 v34, 0xffff0000, v231
	v_fmac_f32_e32 v126, v49, v34
	v_or_b32_e32 v34, 0x400, v68
	v_mov_b32_e32 v35, v69
	v_fmac_f32_e32 v129, v46, v36
	v_lshl_add_u64 v[36:37], v[34:35], 0, v[0:1]
	v_lshlrev_b64 v[36:37], 8, v[36:37]
	v_lshl_add_u64 v[36:37], v[66:67], 0, v[36:37]
	s_waitcnt vmcnt(7)
	v_lshlrev_b32_e32 v38, 16, v232
	v_fmac_f32_e32 v125, v18, v38
	v_and_b32_e32 v18, 0xffff0000, v232
	v_fmac_f32_e32 v124, v19, v18
	v_lshlrev_b32_e32 v18, 16, v233
	v_fmac_f32_e32 v123, v20, v18
	v_and_b32_e32 v18, 0xffff0000, v233
	v_fmac_f32_e32 v122, v21, v18
	v_or_b32_e32 v20, 0x500, v68
	v_mov_b32_e32 v21, v69
	v_lshl_add_u64 v[18:19], v[20:21], 0, v[0:1]
	v_lshlrev_b64 v[18:19], 8, v[18:19]
	v_lshl_add_u64 v[18:19], v[66:67], 0, v[18:19]
	s_waitcnt vmcnt(6)
	v_lshlrev_b32_e32 v36, 16, v234
	v_and_b32_e32 v18, 0xffff0000, v234
	v_fmac_f32_e32 v120, v23, v18
	v_lshlrev_b32_e32 v18, 16, v235
	v_fmac_f32_e32 v119, v24, v18
	v_and_b32_e32 v18, 0xffff0000, v235
	v_fmac_f32_e32 v118, v25, v18
	v_or_b32_e32 v18, 0x600, v68
	v_mov_b32_e32 v19, v69
	v_fmac_f32_e32 v121, v22, v36
	v_lshl_add_u64 v[22:23], v[18:19], 0, v[0:1]
	v_lshlrev_b64 v[22:23], 8, v[22:23]
	v_lshl_add_u64 v[22:23], v[66:67], 0, v[22:23]
	v_or_b32_e32 v68, 0x700, v68
	s_waitcnt vmcnt(5)
	v_lshlrev_b32_e32 v24, 16, v236
	v_and_b32_e32 v22, 0xffff0000, v236
	v_fmac_f32_e32 v116, v27, v22
	v_lshlrev_b32_e32 v22, 16, v237
	v_fmac_f32_e32 v115, v28, v22
	v_and_b32_e32 v22, 0xffff0000, v237
	v_fmac_f32_e32 v114, v29, v22
	v_lshl_add_u64 v[22:23], v[68:69], 0, v[0:1]
	v_lshlrev_b64 v[22:23], 8, v[22:23]
	v_lshl_add_u64 v[22:23], v[66:67], 0, v[22:23]
	v_fmac_f32_e32 v117, v26, v24
	s_waitcnt vmcnt(4)
	v_lshlrev_b32_e32 v0, 16, v238
	v_fmac_f32_e32 v113, v30, v0
	v_and_b32_e32 v0, 0xffff0000, v238
	v_fmac_f32_e32 v112, v31, v0
	v_lshlrev_b32_e32 v0, 16, v239
	v_fmac_f32_e32 v111, v32, v0
	v_and_b32_e32 v0, 0xffff0000, v239
	v_lshl_add_u64 v[22:23], v[34:35], 0, v[50:51]
	v_lshlrev_b64 v[22:23], 8, v[22:23]
	v_lshl_add_u64 v[22:23], v[66:67], 0, v[22:23]
	v_fmac_f32_e32 v110, v33, v0
	s_waitcnt vmcnt(3)
	v_lshlrev_b32_e32 v0, 16, v240
	v_fmac_f32_e32 v109, v2, v0
	v_and_b32_e32 v0, 0xffff0000, v240
	v_fmac_f32_e32 v108, v3, v0
	v_lshl_add_u64 v[2:3], v[20:21], 0, v[50:51]
	v_lshlrev_b64 v[2:3], 8, v[2:3]
	v_lshl_add_u64 v[2:3], v[66:67], 0, v[2:3]
	v_lshlrev_b32_e32 v0, 16, v241
	v_fmac_f32_e32 v107, v4, v0
	v_and_b32_e32 v0, 0xffff0000, v241
	v_fmac_f32_e32 v106, v5, v0
	s_waitcnt vmcnt(2)
	v_lshlrev_b32_e32 v0, 16, v242
	v_fmac_f32_e32 v105, v6, v0
	v_and_b32_e32 v0, 0xffff0000, v242
	v_fmac_f32_e32 v104, v7, v0
	v_lshlrev_b32_e32 v0, 16, v243
	v_fmac_f32_e32 v103, v8, v0
	v_and_b32_e32 v0, 0xffff0000, v243
	v_lshl_add_u64 v[2:3], v[18:19], 0, v[50:51]
	v_lshlrev_b64 v[2:3], 8, v[2:3]
	v_lshl_add_u64 v[2:3], v[66:67], 0, v[2:3]
	v_fmac_f32_e32 v102, v9, v0
	s_waitcnt vmcnt(1)
	v_lshlrev_b32_e32 v0, 16, v244
	v_fmac_f32_e32 v101, v10, v0
	v_and_b32_e32 v0, 0xffff0000, v244
	v_fmac_f32_e32 v100, v11, v0
	v_lshlrev_b32_e32 v0, 16, v245
	v_fmac_f32_e32 v99, v12, v0
	v_and_b32_e32 v0, 0xffff0000, v245
	v_lshl_add_u64 v[2:3], v[68:69], 0, v[50:51]
	v_lshlrev_b64 v[2:3], 8, v[2:3]
	v_lshl_add_u64 v[2:3], v[66:67], 0, v[2:3]
	v_fmac_f32_e32 v98, v13, v0
	s_waitcnt vmcnt(0)
	v_lshlrev_b32_e32 v0, 16, v246
	v_fmac_f32_e32 v97, v14, v0
	v_and_b32_e32 v0, 0xffff0000, v246
	v_fmac_f32_e32 v96, v15, v0
	v_lshlrev_b32_e32 v0, 16, v247
	v_fmac_f32_e32 v95, v16, v0
	v_and_b32_e32 v0, 0xffff0000, v247
	v_fmac_f32_e32 v94, v17, v0
	s_cbranch_scc0 .LBB0_134
; DI u16 f2bf(float x) { return (u16)(pack2(x, 0.f) & 0xffffu); }
; DI int crow(int i, int h) { return (i & 3) + 8 * (i >> 2) + 4 * h; }
; DI void phase_m4b(const Params& p, int l, char* smem) {
;     ...
;     EPI_IDS
; #pragma unroll
;     for (int ms = 0; ms < 2; ++ms)
; #pragma unroll
;       for (int ns = 0; ns < 2; ++ns)
; #pragma unroll
;         for (int i = 0; i < 16; ++i) {
;           const size_t row = (size_t)mt * 256 + wm * 64 + ms * 32 + crow(i, lh);
;           mg[row * D + nt * 128 + wn * 64 + ns * 32 + lr] = f2bf(accm[ms][ns][i]);
;         }
	v_mov_b32_e32 v0, v196
	s_lshl_b32 s4, s36, 1
	v_ashrrev_i32_e32 v2, 1, v0
	v_and_b32_e32 v2, 0xffffffc0, v2
	v_and_b32_e32 v4, 64, v0
	v_and_b32_e32 v6, 31, v0
	v_ashrrev_i32_e32 v3, 31, v2
	v_lshrrev_b32_e32 v0, 3, v0
	s_add_u32 s4, s18, s4
	v_lshl_add_u64 v[2:3], v[2:3], 0, s[62:63]
	v_and_b32_e32 v38, 4, v0
	s_addc_u32 s5, s19, 0
	v_lshlrev_b32_e32 v0, 1, v4
	v_lshl_add_u64 v[4:5], s[4:5], 0, v[0:1]
	v_lshlrev_b32_e32 v0, 1, v6
	v_or_b32_e32 v6, v2, v38
	v_mov_b32_e32 v7, v3
	v_lshl_add_u64 v[4:5], v[4:5], 0, v[0:1]
	v_lshlrev_b64 v[6:7], 11, v[6:7]
	v_cvt_pk_bf16_f32 v0, v158, s0
	v_lshl_add_u64 v[6:7], v[4:5], 0, v[6:7]
	global_store_short v[6:7], v0, off
	v_or_b32_e32 v0, 1, v38
	v_or_b32_e32 v8, v2, v0
	v_mov_b32_e32 v9, v3
	v_lshlrev_b64 v[8:9], 11, v[8:9]
	v_cvt_pk_bf16_f32 v10, v157, s0
	v_lshl_add_u64 v[8:9], v[4:5], 0, v[8:9]
	v_or_b32_e32 v39, 2, v38
	global_store_short v[8:9], v10, off
	v_or_b32_e32 v10, v2, v39
	v_mov_b32_e32 v11, v3
	v_lshlrev_b64 v[10:11], 11, v[10:11]
	v_cvt_pk_bf16_f32 v12, v156, s0
	v_lshl_add_u64 v[10:11], v[4:5], 0, v[10:11]
	v_or_b32_e32 v40, 3, v38
	global_store_short v[10:11], v12, off
	v_or_b32_e32 v12, v2, v40
	v_mov_b32_e32 v13, v3
	v_lshlrev_b64 v[12:13], 11, v[12:13]
	v_cvt_pk_bf16_f32 v14, v155, s0
	v_lshl_add_u64 v[12:13], v[4:5], 0, v[12:13]
	v_or_b32_e32 v41, 8, v38
	global_store_short v[12:13], v14, off
	v_or_b32_e32 v14, v2, v41
	v_mov_b32_e32 v15, v3
	v_lshlrev_b64 v[14:15], 11, v[14:15]
	v_cvt_pk_bf16_f32 v16, v153, s0
	v_lshl_add_u64 v[14:15], v[4:5], 0, v[14:15]
	v_or_b32_e32 v42, 9, v38
	global_store_short v[14:15], v16, off
	v_or_b32_e32 v16, v2, v42
	v_mov_b32_e32 v17, v3
	v_lshlrev_b64 v[16:17], 11, v[16:17]
	v_cvt_pk_bf16_f32 v18, v152, s0
	v_lshl_add_u64 v[16:17], v[4:5], 0, v[16:17]
	v_or_b32_e32 v43, 10, v38
	global_store_short v[16:17], v18, off
	v_or_b32_e32 v18, v2, v43
	v_mov_b32_e32 v19, v3
	v_lshlrev_b64 v[18:19], 11, v[18:19]
	v_cvt_pk_bf16_f32 v20, v151, s0
	v_lshl_add_u64 v[18:19], v[4:5], 0, v[18:19]
	v_or_b32_e32 v44, 11, v38
	global_store_short v[18:19], v20, off
	v_or_b32_e32 v20, v2, v44
	v_mov_b32_e32 v21, v3
	v_lshlrev_b64 v[20:21], 11, v[20:21]
	v_cvt_pk_bf16_f32 v22, v150, s0
	v_lshl_add_u64 v[20:21], v[4:5], 0, v[20:21]
	v_or_b32_e32 v45, 16, v38
	global_store_short v[20:21], v22, off
	v_or_b32_e32 v22, v2, v45
	v_mov_b32_e32 v23, v3
	v_lshlrev_b64 v[22:23], 11, v[22:23]
	v_cvt_pk_bf16_f32 v24, v149, s0
	v_lshl_add_u64 v[22:23], v[4:5], 0, v[22:23]
	v_or_b32_e32 v46, 17, v38
	global_store_short v[22:23], v24, off
	v_or_b32_e32 v24, v2, v46
	v_mov_b32_e32 v25, v3
	v_lshlrev_b64 v[24:25], 11, v[24:25]
	v_cvt_pk_bf16_f32 v26, v148, s0
	v_lshl_add_u64 v[24:25], v[4:5], 0, v[24:25]
	v_or_b32_e32 v47, 18, v38
	global_store_short v[24:25], v26, off
	v_or_b32_e32 v26, v2, v47
	v_mov_b32_e32 v27, v3
	v_lshlrev_b64 v[26:27], 11, v[26:27]
	v_cvt_pk_bf16_f32 v28, v147, s0
	v_lshl_add_u64 v[26:27], v[4:5], 0, v[26:27]
	v_or_b32_e32 v48, 19, v38
	global_store_short v[26:27], v28, off
	v_or_b32_e32 v28, v2, v48
	v_mov_b32_e32 v29, v3
	v_lshlrev_b64 v[28:29], 11, v[28:29]
	v_cvt_pk_bf16_f32 v30, v146, s0
	v_lshl_add_u64 v[28:29], v[4:5], 0, v[28:29]
	v_or_b32_e32 v49, 24, v38
	global_store_short v[28:29], v30, off
	v_or_b32_e32 v30, v2, v49
	v_mov_b32_e32 v31, v3
	v_lshlrev_b64 v[30:31], 11, v[30:31]
	v_cvt_pk_bf16_f32 v32, v145, s0
	v_lshl_add_u64 v[30:31], v[4:5], 0, v[30:31]
	v_or_b32_e32 v50, 25, v38
	global_store_short v[30:31], v32, off
	v_or_b32_e32 v32, v2, v50
	v_mov_b32_e32 v33, v3
	v_lshlrev_b64 v[32:33], 11, v[32:33]
	v_cvt_pk_bf16_f32 v34, v144, s0
	v_lshl_add_u64 v[32:33], v[4:5], 0, v[32:33]
	v_or_b32_e32 v51, 26, v38
	global_store_short v[32:33], v34, off
	v_or_b32_e32 v34, v2, v51
	v_mov_b32_e32 v35, v3
	v_lshlrev_b64 v[34:35], 11, v[34:35]
	v_cvt_pk_bf16_f32 v36, v143, s0
	v_lshl_add_u64 v[34:35], v[4:5], 0, v[34:35]
	v_or_b32_e32 v52, 27, v38
	global_store_short v[34:35], v36, off
	v_or_b32_e32 v36, v2, v52
	v_mov_b32_e32 v37, v3
	v_lshlrev_b64 v[36:37], 11, v[36:37]
	v_cvt_pk_bf16_f32 v53, v142, s0
	v_lshl_add_u64 v[36:37], v[4:5], 0, v[36:37]
	global_store_short v[36:37], v53, off
	v_cvt_pk_bf16_f32 v53, v141, s0
	global_store_short v[6:7], v53, off offset:64
	v_cvt_pk_bf16_f32 v6, v140, s0
	global_store_short v[8:9], v6, off offset:64
	v_cvt_pk_bf16_f32 v6, v139, s0
	global_store_short v[10:11], v6, off offset:64
	v_cvt_pk_bf16_f32 v6, v138, s0
	global_store_short v[12:13], v6, off offset:64
	v_cvt_pk_bf16_f32 v6, v137, s0
	global_store_short v[14:15], v6, off offset:64
	v_cvt_pk_bf16_f32 v6, v136, s0
	global_store_short v[16:17], v6, off offset:64
	v_cvt_pk_bf16_f32 v6, v135, s0
	global_store_short v[18:19], v6, off offset:64
	v_cvt_pk_bf16_f32 v6, v134, s0
	global_store_short v[20:21], v6, off offset:64
	v_cvt_pk_bf16_f32 v6, v133, s0
; DI u16 f2bf(float x) { return (u16)(pack2(x, 0.f) & 0xffffu); }
; DI int crow(int i, int h) { return (i & 3) + 8 * (i >> 2) + 4 * h; }
; DI void phase_m4b(const Params& p, int l, char* smem) {
;     ...
;     EPI_IDS
; #pragma unroll
;     for (int ms = 0; ms < 2; ++ms)
; #pragma unroll
;       for (int ns = 0; ns < 2; ++ns)
; #pragma unroll
;         for (int i = 0; i < 16; ++i) {
;           const size_t row = (size_t)mt * 256 + wm * 64 + ms * 32 + crow(i, lh);
;           mg[row * D + nt * 128 + wn * 64 + ns * 32 + lr] = f2bf(accm[ms][ns][i]);
;         }
	global_store_short v[22:23], v6, off offset:64
	v_cvt_pk_bf16_f32 v6, v132, s0
	global_store_short v[24:25], v6, off offset:64
	v_cvt_pk_bf16_f32 v6, v131, s0
	global_store_short v[26:27], v6, off offset:64
	v_cvt_pk_bf16_f32 v6, v130, s0
	global_store_short v[28:29], v6, off offset:64
	v_cvt_pk_bf16_f32 v6, v129, s0
	global_store_short v[30:31], v6, off offset:64
	v_cvt_pk_bf16_f32 v6, v128, s0
	global_store_short v[32:33], v6, off offset:64
	v_cvt_pk_bf16_f32 v6, v127, s0
	global_store_short v[34:35], v6, off offset:64
	v_cvt_pk_bf16_f32 v6, v126, s0
	global_store_short v[36:37], v6, off offset:64
	v_or_b32_e32 v36, 32, v2
	v_or_b32_e32 v2, v36, v38
	v_lshlrev_b64 v[6:7], 11, v[2:3]
	v_cvt_pk_bf16_f32 v8, v125, s0
	v_lshl_add_u64 v[6:7], v[4:5], 0, v[6:7]
	v_or_b32_e32 v2, v36, v0
	global_store_short v[6:7], v8, off
	v_lshlrev_b64 v[8:9], 11, v[2:3]
	v_or_b32_e32 v2, v36, v39
	v_cvt_pk_bf16_f32 v0, v124, s0
	v_lshl_add_u64 v[8:9], v[4:5], 0, v[8:9]
	v_lshlrev_b64 v[10:11], 11, v[2:3]
	v_or_b32_e32 v2, v36, v40
	global_store_short v[8:9], v0, off
	v_cvt_pk_bf16_f32 v0, v123, s0
	v_lshl_add_u64 v[10:11], v[4:5], 0, v[10:11]
	v_lshlrev_b64 v[12:13], 11, v[2:3]
	v_or_b32_e32 v2, v36, v41
	global_store_short v[10:11], v0, off
	v_cvt_pk_bf16_f32 v0, v122, s0
	v_lshl_add_u64 v[12:13], v[4:5], 0, v[12:13]
	v_lshlrev_b64 v[14:15], 11, v[2:3]
	v_or_b32_e32 v2, v36, v42
	global_store_short v[12:13], v0, off
	v_cvt_pk_bf16_f32 v0, v121, s0
	v_lshl_add_u64 v[14:15], v[4:5], 0, v[14:15]
	v_lshlrev_b64 v[16:17], 11, v[2:3]
	v_or_b32_e32 v2, v36, v43
	global_store_short v[14:15], v0, off
	v_cvt_pk_bf16_f32 v0, v120, s0
	v_lshl_add_u64 v[16:17], v[4:5], 0, v[16:17]
	v_lshlrev_b64 v[18:19], 11, v[2:3]
	v_or_b32_e32 v2, v36, v44
	global_store_short v[16:17], v0, off
	v_cvt_pk_bf16_f32 v0, v119, s0
	v_lshl_add_u64 v[18:19], v[4:5], 0, v[18:19]
	v_lshlrev_b64 v[20:21], 11, v[2:3]
	v_or_b32_e32 v2, v36, v45
	global_store_short v[18:19], v0, off
	v_cvt_pk_bf16_f32 v0, v118, s0
	v_lshl_add_u64 v[20:21], v[4:5], 0, v[20:21]
	v_lshlrev_b64 v[22:23], 11, v[2:3]
	v_or_b32_e32 v2, v36, v46
	global_store_short v[20:21], v0, off
	v_cvt_pk_bf16_f32 v0, v117, s0
	v_lshl_add_u64 v[22:23], v[4:5], 0, v[22:23]
	v_lshlrev_b64 v[24:25], 11, v[2:3]
	v_or_b32_e32 v2, v36, v47
	global_store_short v[22:23], v0, off
	v_cvt_pk_bf16_f32 v0, v116, s0
	v_lshl_add_u64 v[24:25], v[4:5], 0, v[24:25]
	v_lshlrev_b64 v[26:27], 11, v[2:3]
	v_or_b32_e32 v2, v36, v48
	global_store_short v[24:25], v0, off
	v_cvt_pk_bf16_f32 v0, v115, s0
	v_lshl_add_u64 v[26:27], v[4:5], 0, v[26:27]
	v_lshlrev_b64 v[28:29], 11, v[2:3]
	v_or_b32_e32 v2, v36, v49
	global_store_short v[26:27], v0, off
	v_cvt_pk_bf16_f32 v0, v114, s0
	v_lshl_add_u64 v[28:29], v[4:5], 0, v[28:29]
	v_lshlrev_b64 v[30:31], 11, v[2:3]
	v_or_b32_e32 v2, v36, v50
	global_store_short v[28:29], v0, off
	v_cvt_pk_bf16_f32 v0, v113, s0
	v_lshl_add_u64 v[30:31], v[4:5], 0, v[30:31]
	v_lshlrev_b64 v[32:33], 11, v[2:3]
	v_or_b32_e32 v2, v36, v51
	global_store_short v[30:31], v0, off
	v_cvt_pk_bf16_f32 v0, v112, s0
	v_lshl_add_u64 v[32:33], v[4:5], 0, v[32:33]
	v_lshlrev_b64 v[34:35], 11, v[2:3]
	v_or_b32_e32 v2, v36, v52
	global_store_short v[32:33], v0, off
	v_cvt_pk_bf16_f32 v0, v111, s0
	v_lshl_add_u64 v[34:35], v[4:5], 0, v[34:35]
	v_lshlrev_b64 v[2:3], 11, v[2:3]
	global_store_short v[34:35], v0, off
	v_cvt_pk_bf16_f32 v0, v110, s0
	v_lshl_add_u64 v[2:3], v[4:5], 0, v[2:3]
	global_store_short v[2:3], v0, off
	v_cvt_pk_bf16_f32 v0, v109, s0
	global_store_short v[6:7], v0, off offset:64
	v_cvt_pk_bf16_f32 v0, v108, s0
	global_store_short v[8:9], v0, off offset:64
	v_cvt_pk_bf16_f32 v0, v107, s0
	global_store_short v[10:11], v0, off offset:64
	v_cvt_pk_bf16_f32 v0, v106, s0
	global_store_short v[12:13], v0, off offset:64
	v_cvt_pk_bf16_f32 v0, v105, s0
	global_store_short v[14:15], v0, off offset:64
	v_cvt_pk_bf16_f32 v0, v104, s0
	global_store_short v[16:17], v0, off offset:64
	v_cvt_pk_bf16_f32 v0, v103, s0
	global_store_short v[18:19], v0, off offset:64
	v_cvt_pk_bf16_f32 v0, v102, s0
	global_store_short v[20:21], v0, off offset:64
	v_cvt_pk_bf16_f32 v0, v101, s0
	global_store_short v[22:23], v0, off offset:64
	v_cvt_pk_bf16_f32 v0, v100, s0
	global_store_short v[24:25], v0, off offset:64
	v_cvt_pk_bf16_f32 v0, v99, s0
	global_store_short v[26:27], v0, off offset:64
	v_cvt_pk_bf16_f32 v0, v98, s0
	global_store_short v[28:29], v0, off offset:64
	v_cvt_pk_bf16_f32 v0, v97, s0
	global_store_short v[30:31], v0, off offset:64
	v_cvt_pk_bf16_f32 v0, v96, s0
	global_store_short v[32:33], v0, off offset:64
	v_cvt_pk_bf16_f32 v0, v95, s0
	s_add_i32 s31, s31, s58
	s_add_i32 s29, s29, s58
	global_store_short v[34:35], v0, off offset:64
	v_cvt_pk_bf16_f32 v0, v94, s0
	s_cmp_gt_u32 s31, 63
	global_store_short v[2:3], v0, off offset:64
	s_cbranch_scc0 .LBB0_133
